# scan y reduction: selector value kept in a register across chunks, copied into the MFMA operand (4 moves instead of a 15-instruction build)
# speedup vs baseline: 1.0117x; 1.0024x over previous
.LBB0_407:
	s_or_b64 exec, exec, s[12:13]
	v_add_f32_e32 v26, v32, v33
	v_sqrt_f32_e32 v26, v26
	s_waitcnt vmcnt(12)
	v_cvt_f32_f16_sdwa v27, v63 dst_sel:DWORD dst_unused:UNUSED_PAD src0_sel:WORD_1
	v_cvt_f32_f16_sdwa v21, v62 dst_sel:DWORD dst_unused:UNUSED_PAD src0_sel:WORD_1
	v_cvt_f32_f16_e32 v20, v62
	v_max_f32_e32 v26, 0x2b8cbccc, v26
	v_rcp_f32_e32 v26, v26
	v_cvt_f32_f16_e32 v28, v63
	v_cndmask_b32_e64 v29, v27, 1.0, s[0:1]
	s_lshl_b32 s92, s58, 5
	v_pk_mul_f32 v[30:31], v[16:17], v[26:27] op_sel_hi:[1,0]
	v_pk_mul_f32 v[26:27], v[18:19], v[26:27] op_sel_hi:[1,0]
	v_cndmask_b32_e64 v20, v20, 1.0, s[0:1]
	v_cndmask_b32_e64 v28, v28, 1.0, s[0:1]
	v_cndmask_b32_e64 v21, v21, 1.0, s[0:1]
	v_pk_mul_f32 v[14:15], v[14:15], v[30:31]
	v_pk_mul_f32 v[12:13], v[12:13], v[26:27]
	s_lshl_b32 s12, s90, 2
	v_pk_mul_f32 v[18:19], v[28:29], v[30:31] neg_lo:[0,1] neg_hi:[0,1]
	v_pk_mul_f32 v[16:17], v[20:21], v[26:27] neg_lo:[0,1] neg_hi:[0,1]
	v_pk_mul_f32 v[14:15], v[24:25], v[14:15]
	v_pk_mul_f32 v[12:13], v[22:23], v[12:13]
	v_lshl_add_u64 v[84:85], s[60:61], 0, v[42:43]
	v_lshl_add_u64 v[86:87], s[28:29], 0, v[42:43]
	v_lshl_add_u64 v[88:89], s[14:15], 0, v[42:43]
	s_add_u32 s58, s44, s12
	v_mov_b32_e32 v42, v43
	ds_write_b128 v41, v[16:19] offset:12288
	ds_write_b128 v41, v[12:15] offset:16384
	s_addc_u32 s59, s45, 0
	s_mov_b32 s93, 0
	s_mov_b64 s[62:63], 0
	s_mov_b64 s[64:65], -1
	v_mov_b64_e32 v[16:17], v[42:43]
	v_mov_b64_e32 v[18:19], v[42:43]
	v_mov_b64_e32 v[12:13], v[42:43]
	v_mov_b64_e32 v[14:15], v[42:43]
	v_mov_b32_e32 v233, 0
	v_and_b32_e32 v224, 15, v152
	v_mov_b32_e32 v216, 0
	v_mov_b32_e32 v225, 0x3c00
	v_cmp_eq_u32_e32 vcc, 0, v224
	v_mov_b32_e32 v226, 0x3c000000
	s_nop 1
	v_cndmask_b32_e32 v216, v216, v225, vcc
	v_cmp_eq_u32_e32 vcc, 1, v224
	s_nop 1
	v_cndmask_b32_e32 v216, v216, v226, vcc
	s_nop 0
	v_mov_b32_e32 v223, v216
	v_lshrrev_b32_e32 v224, 4, v152
	v_mul_u32_u24_e32 v224, 0x3f0, v224
	v_sub_u32_e32 v222, v105, v224
	v_lshlrev_b32_e32 v232, 1, v40
	v_mov_b32_e32 v229, s11
	v_mov_b32_e32 v227, s33
	v_add_u32_e32 v224, -16, v46
	v_cmp_gt_i32_e32 vcc, s87, v224
	v_add_u32_e32 v226, 0xffffbf80, v224
	v_ashrrev_i32_e32 v225, 31, v224
	v_cndmask_b32_e32 v224, v226, v224, vcc
	v_mov_b32_e32 v226, s10
	v_cndmask_b32_e32 v225, 0, v225, vcc
	v_cndmask_b32_e32 v227, v226, v227, vcc
	v_mov_b32_e32 v226, s3
	v_cndmask_b32_e32 v226, v226, v229, vcc
	v_lshlrev_b64 v[224:225], 11, v[224:225]
	v_lshl_add_u64 v[224:225], v[226:227], 0, v[224:225]
	s_lshl_b32 s42, s57, 1
	v_lshl_add_u64 v[224:225], v[224:225], 0, s[42:43]
	s_lshl_b32 s42, s92, 1
	v_lshl_add_u64 v[224:225], v[224:225], 0, s[42:43]
	v_lshl_add_u64 v[224:225], v[224:225], 0, v[232:233]
	s_movk_i32 s42, 0x1000
	v_lshl_add_u64 v[220:221], v[224:225], 0, s[42:43]
	s_waitcnt lgkmcnt(0)
	s_barrier
	s_branch .LBB0_410

.LBB0_412:
	s_cmp_lg_u32 s93, 0
	s_cselect_b64 s[12:13], -1, 0
	s_and_b64 s[50:51], s[12:13], s[4:5]
	s_and_saveexec_b64 s[12:13], s[50:51]
	s_cbranch_execz .LBB0_414
	s_add_i32 s42, s93, -1
	s_lshl_b32 s50, s42, 14
	s_and_b32 s50, s50, 0x4000
	v_add_u32_e32 v134, s50, v222
	ds_read_b128 v[116:119], v134 offset:45056
	ds_read_b128 v[120:123], v134 offset:46080
	ds_read_b128 v[124:127], v134 offset:47104
	ds_read_b128 v[24:27], v134 offset:48128
	s_mov_b32 s42, 0x8000
	v_lshl_add_u64 v[220:221], v[220:221], 0, s[42:43]
	v_mov_b32_e32 v130, v223
	v_mov_b32_e32 v131, v223
	v_mov_b32_e32 v132, v223
	v_mov_b32_e32 v133, v223
	s_nop 1
	s_waitcnt lgkmcnt(3)
	v_mfma_f32_16x16x32_f16 v[28:31], v[130:133], v[116:119], 0
	s_waitcnt lgkmcnt(2)
	v_mfma_f32_16x16x32_f16 v[32:35], v[130:133], v[120:123], 0
	s_waitcnt lgkmcnt(1)
	v_mfma_f32_16x16x32_f16 v[116:119], v[130:133], v[124:127], 0
	s_waitcnt lgkmcnt(0)
	v_mfma_f32_16x16x32_f16 v[120:123], v[130:133], v[24:27], 0
	s_mov_b64 s[50:51], exec
	s_nop 7
	v_cvt_pk_f16_f32 v28, v28, v29
	v_cvt_pk_f16_f32 v32, v32, v33
	v_cvt_pk_f16_f32 v116, v116, v117
	v_cvt_pk_f16_f32 v120, v120, v121
	s_mov_b64 exec, 0xffff
	global_store_dword v[220:221], v28, off offset:-4096
	global_store_dword v[220:221], v32, off offset:-2048
	global_store_dword v[220:221], v116, off
	global_store_dword v[220:221], v120, off offset:2048
	s_mov_b64 exec, s[50:51]

.LBB0_423:
	s_and_saveexec_b64 s[12:13], s[4:5]
	s_cbranch_execz .LBB0_425
	s_mulk_i32 s42, 0xe800
	s_add_i32 s97, s97, s42
	v_add_u32_e32 v134, s97, v222
	ds_read_b128 v[116:119], v134 offset:45056
	ds_read_b128 v[120:123], v134 offset:46080
	ds_read_b128 v[124:127], v134 offset:47104
	ds_read_b128 v[28:31], v134 offset:48128
	s_mov_b32 s42, 0x8000
	v_lshl_add_u64 v[220:221], v[220:221], 0, s[42:43]
	v_mov_b32_e32 v130, v223
	v_mov_b32_e32 v131, v223
	v_mov_b32_e32 v132, v223
	v_mov_b32_e32 v133, v223
	s_nop 1
	s_waitcnt lgkmcnt(3)
	v_mfma_f32_16x16x32_f16 v[90:93], v[130:133], v[116:119], 0
	s_waitcnt lgkmcnt(2)
	v_mfma_f32_16x16x32_f16 v[32:35], v[130:133], v[120:123], 0
	s_waitcnt lgkmcnt(1)
	v_mfma_f32_16x16x32_f16 v[116:119], v[130:133], v[124:127], 0
	s_waitcnt lgkmcnt(0)
	v_mfma_f32_16x16x32_f16 v[120:123], v[130:133], v[28:31], 0
	s_mov_b64 s[50:51], exec
	s_nop 7
	v_cvt_pk_f16_f32 v90, v90, v91
	v_cvt_pk_f16_f32 v32, v32, v33
	v_cvt_pk_f16_f32 v116, v116, v117
	v_cvt_pk_f16_f32 v120, v120, v121
	s_mov_b64 exec, 0xffff
	global_store_dword v[220:221], v90, off offset:-4096
	global_store_dword v[220:221], v32, off offset:-2048
	global_store_dword v[220:221], v116, off
	global_store_dword v[220:221], v120, off offset:2048
	s_mov_b64 exec, s[50:51]

.LBB0_434:
	s_and_saveexec_b64 s[12:13], s[4:5]
	s_cbranch_execz .LBB0_436
	s_lshl_b32 s42, s96, 14
	s_and_b32 s42, s42, 0x4000
	v_add_u32_e32 v134, s42, v222
	ds_read_b128 v[116:119], v134 offset:45056
	ds_read_b128 v[120:123], v134 offset:46080
	ds_read_b128 v[124:127], v134 offset:47104
	ds_read_b128 v[20:23], v134 offset:48128
	s_mov_b32 s42, 0x8000
	v_lshl_add_u64 v[220:221], v[220:221], 0, s[42:43]
	v_mov_b32_e32 v130, v223
	v_mov_b32_e32 v131, v223
	v_mov_b32_e32 v132, v223
	v_mov_b32_e32 v133, v223
	s_nop 1
	s_waitcnt lgkmcnt(3)
	v_mfma_f32_16x16x32_f16 v[24:27], v[130:133], v[116:119], 0
	s_waitcnt lgkmcnt(2)
	v_mfma_f32_16x16x32_f16 v[92:95], v[130:133], v[120:123], 0
	s_waitcnt lgkmcnt(1)
	v_mfma_f32_16x16x32_f16 v[116:119], v[130:133], v[124:127], 0
	s_waitcnt lgkmcnt(0)
	v_mfma_f32_16x16x32_f16 v[120:123], v[130:133], v[20:23], 0
	s_mov_b64 s[50:51], exec
	s_nop 7
	v_cvt_pk_f16_f32 v24, v24, v25
	v_cvt_pk_f16_f32 v92, v92, v93
	v_cvt_pk_f16_f32 v116, v116, v117
	v_cvt_pk_f16_f32 v120, v120, v121
	s_mov_b64 exec, 0xffff
	global_store_dword v[220:221], v24, off offset:-4096
	global_store_dword v[220:221], v92, off offset:-2048
	global_store_dword v[220:221], v116, off
	global_store_dword v[220:221], v120, off offset:2048
	s_mov_b64 exec, s[50:51]
